# thin kv tile: MFMA-computing waves at wave priority 3 instead of 2
# baseline (speedup 1.0000x reference)
; template <bool SWAP, class Epi, bool THIN = false> ...
;     ...
;     unsigned ap[4], bp[4];
; #pragma unroll
;     for (int i = 0; i < 4; ++i) {
;       const int r = (tid >> 3) + 64 * i;
;       const int cs = tid & 7;
;       const int c = ((cs ^ ((r >> 1) & 7)) << 3);
;       const int sub = 2 * mt + (r >> 7);
;       const int g = sub / tpg, ti = sub - g * tpg;
;       int rig = ti * step - halo + (r & 127); rig = rig < 0 ? 0 : (rig > grows - 1 ? grows - 1 : rig);
;       ap[i] = (unsigned)((g * a_gstride + a_goff + rig) * lda + c);
;       int br = nt * 256 + r; br = br > N - 1 ? N - 1 : br;
;       bp[i] = (unsigned)(br * K + c);
;     }
;     const bool have_next = false;
;     f32x4 acc[4][8];
; #pragma unroll
;     for (int m = 0; m < 4; ++m)
; #pragma unroll
;       for (int n = 0; n < 8; ++n) acc[m][n] = (f32x4){0.f, 0.f, 0.f, 0.f};
;     if (!pre_issued) {
; #pragma unroll
;       for (int i = 0; i < 4; ++i) { GLDS16(A + (size_t)ap[i], smem + tid * 16 + i * 8192); GLDS16(Bt + (size_t)bp[i], smem + 32768 + tid * 16 + i * 8192); }
;     }
;     pre_issued = have_next;
;     for (int st = 0; st < ns; ++st) {
;       asm volatile("s_waitcnt vmcnt(0)" ::: "memory");
;       __builtin_amdgcn_s_barrier();
;       asm volatile("" ::: "memory");
;       if (st + 1 < ns) {
;         char* nb = smem + ((st + 1) & 1) * 65536;
;         const int ko = (st + 1) * 64;
; #pragma unroll
;         for (int i = 0; i < 4; ++i) { GLDS16(A + (size_t)(ap[i] + ko), nb + tid * 16 + i * 8192); GLDS16(Bt + (size_t)(bp[i] + ko), nb + 32768 + tid * 16 + i * 8192); }
;       }
;       const char* sa = smem + (st & 1) * 65536 + (wr * 64 + fr) * 128;
;       const char* sb = smem + (st & 1) * 65536 + 32768 + (wc * 128 + fr) * 128;
;       if constexpr (THIN) {
;         if (wc == 0) {
; #pragma unroll
;           for (int ks = 0; ks < 2; ++ks) {
;             bf16x8 af[4], bf[2];
; #pragma unroll
;             for (int m = 0; m < 4; ++m) af[m] = *(const bf16x8*)(sa + m * 2048 + (((ks * 4 + fq) ^ swz) << 4));
; #pragma unroll
;             for (int n = 0; n < 2; ++n) bf[n] = *(const bf16x8*)(sb + n * 2048 + (((ks * 4 + fq) ^ swz) << 4));
; #pragma unroll
;             for (int m = 0; m < 4; ++m)
; #pragma unroll
;               for (int n = 0; n < 2; ++n)
;                 acc[m][n] = SWAP ? __builtin_amdgcn_mfma_f32_16x16x32_bf16(bf[n], af[m], acc[m][n], 0, 0, 0)
.LBB0_1525:
	s_ashr_i32 s7, s3, 31
	s_lshr_b32 s7, s7, 29
	s_add_i32 s6, s3, 0x108
	s_add_i32 s7, s3, s7
	s_and_b32 s7, s7, -8
	s_and_b32 s6, s6, 7
	s_or_b32 s6, s7, s6
	s_lshl_b32 s9, s6, 1
	v_add_u32_e32 v2, s9, v57
	v_mul_hi_i32 v4, v2, s33
	v_lshrrev_b32_e32 v5, 31, v4
	v_ashrrev_i32_e32 v4, 2, v4
	v_add_u32_e32 v6, v4, v5
	s_sub_i32 s8, s3, s7
	v_mad_u64_u32 v[4:5], s[6:7], v6, s74, v[2:3]
	v_lshl_or_b32 v2, v4, 7, v58
	v_min_i32_e32 v2, 0x8ff, v2
	v_cmp_lt_i32_e32 vcc, -1, v4
	s_ashr_i32 s46, s8, 3
	s_lshl_b32 s8, s46, 8
	v_cndmask_b32_e32 v2, 0, v2, vcc
	v_mad_u64_u32 v[4:5], s[6:7], v6, s75, v[2:3]
	v_lshl_or_b32 v2, v4, 10, v55
	v_add_u32_e32 v4, s8, v54
	v_min_i32_e32 v4, 31, v4
	v_lshl_or_b32 v38, v4, 10, v55
	v_add_u32_e32 v4, s9, v60
	v_mul_hi_i32 v5, v4, s33
	v_lshrrev_b32_e32 v6, 31, v5
	v_ashrrev_i32_e32 v5, 2, v5
	v_add_u32_e32 v6, v5, v6
	v_mad_u64_u32 v[4:5], s[6:7], v6, s74, v[4:5]
	v_lshl_or_b32 v5, v4, 7, v61
	v_min_i32_e32 v5, 0x8ff, v5
	v_cmp_lt_i32_e32 vcc, -1, v4
	v_add_u32_e32 v8, s9, v65
	v_lshl_add_u64 v[46:47], v[2:3], 1, s[36:37]
	v_cndmask_b32_e32 v4, 0, v5, vcc
	v_mad_u64_u32 v[4:5], s[6:7], v6, s75, v[4:5]
	v_add_u32_e32 v5, s8, v59
	v_min_i32_e32 v5, 31, v5
	v_add_u32_e32 v6, s9, v63
	v_lshl_or_b32 v40, v5, 10, v55
	v_mul_hi_i32 v5, v6, s33
	v_lshrrev_b32_e32 v7, 31, v5
	v_ashrrev_i32_e32 v5, 2, v5
	v_add_u32_e32 v5, v5, v7
	v_mad_u64_u32 v[6:7], s[6:7], v5, s74, v[6:7]
	v_lshl_or_b32 v7, v6, 7, v58
	v_min_i32_e32 v7, 0x8ff, v7
	v_cmp_lt_i32_e32 vcc, -1, v6
	v_mov_b32_e32 v39, v3
	v_lshl_or_b32 v4, v4, 10, v55
	v_cndmask_b32_e32 v6, 0, v7, vcc
	v_mad_u64_u32 v[6:7], s[6:7], v5, s75, v[6:7]
	v_add_u32_e32 v5, s8, v62
	v_min_i32_e32 v5, 31, v5
	v_lshl_or_b32 v42, v5, 10, v55
	v_mul_hi_i32 v5, v8, s33
	v_lshrrev_b32_e32 v7, 31, v5
	v_ashrrev_i32_e32 v5, 2, v5
	v_add_u32_e32 v5, v5, v7
	v_mad_u64_u32 v[8:9], s[6:7], v5, s74, v[8:9]
	v_lshl_or_b32 v7, v8, 7, v66
	v_min_i32_e32 v7, 0x8ff, v7
	v_cmp_lt_i32_e32 vcc, -1, v8
	v_lshl_add_u64 v[10:11], v[38:39], 1, s[18:19]
	v_mov_b32_e32 v41, v3
	v_cndmask_b32_e32 v8, 0, v7, vcc
	v_mad_u64_u32 v[8:9], s[6:7], v5, s75, v[8:9]
	v_add_u32_e32 v5, s8, v64
	v_readfirstlane_b32 s6, v56
	v_min_i32_e32 v5, 31, v5
	s_mov_b32 m0, s6
	v_readfirstlane_b32 s6, v67
	v_lshl_or_b32 v44, v5, 10, v55
	global_load_lds_dwordx4 v[46:47], off
	s_mov_b32 m0, s6
	v_mov_b32_e32 v5, v3
	v_readfirstlane_b32 s6, v68
	global_load_lds_dwordx4 v[10:11], off
	v_lshl_add_u64 v[48:49], v[4:5], 1, s[36:37]
	s_mov_b32 m0, s6
	v_readfirstlane_b32 s6, v69
	v_lshl_or_b32 v6, v6, 10, v55
	global_load_lds_dwordx4 v[48:49], off
	v_lshl_add_u64 v[4:5], v[40:41], 1, s[18:19]
	s_mov_b32 m0, s6
	v_mov_b32_e32 v7, v3
	v_readfirstlane_b32 s6, v70
	v_lshl_add_u64 v[50:51], v[6:7], 1, s[36:37]
	s_mov_b32 m0, s6
	v_mov_b32_e32 v43, v3
	v_readfirstlane_b32 s6, v71
	v_lshl_or_b32 v8, v8, 10, v55
	global_load_lds_dwordx4 v[50:51], off
	v_lshl_add_u64 v[4:5], v[42:43], 1, s[18:19]
	s_mov_b32 m0, s6
	v_mov_b32_e32 v9, v3
	v_readfirstlane_b32 s6, v72
	v_lshl_add_u64 v[52:53], v[8:9], 1, s[36:37]
	s_mov_b32 m0, s6
	v_mov_b32_e32 v45, v3
	v_readfirstlane_b32 s6, v73
	global_load_lds_dwordx4 v[52:53], off
	v_lshl_add_u64 v[4:5], v[44:45], 1, s[18:19]
	s_mov_b32 m0, s6
	v_readfirstlane_b32 s6, v74
	v_readfirstlane_b32 s6, v56
	s_add_i32 m0, s6, 0x10000
	v_lshl_add_u64 v[4:5], v[46:47], 0, s[22:23]
	global_load_lds_dwordx4 v[4:5], off
	v_or_b32_e32 v2, 64, v38
	s_add_i32 m0, s6, 0x18000
	v_lshl_add_u64 v[4:5], v[2:3], 1, s[18:19]
	global_load_lds_dwordx4 v[4:5], off
	s_add_i32 m0, s6, 0x12000
	v_lshl_add_u64 v[4:5], v[48:49], 0, s[22:23]
	global_load_lds_dwordx4 v[4:5], off
	s_add_i32 m0, s6, 0x14000
	v_lshl_add_u64 v[4:5], v[50:51], 0, s[22:23]
	global_load_lds_dwordx4 v[4:5], off
	s_add_i32 m0, s6, 0x16000
	v_lshl_add_u64 v[4:5], v[52:53], 0, s[22:23]
	global_load_lds_dwordx4 v[4:5], off
	s_waitcnt vmcnt(5)
	s_barrier
	v_readfirstlane_b32 s6, v56
	s_add_i32 m0, s6, 0x1a000
	v_lshl_add_u64 v[4:5], v[46:47], 0, s[24:25]
	global_load_lds_dwordx4 v[4:5], off
	v_or_b32_e32 v2, 0x80, v38
	s_add_i32 m0, s6, 0x22000
	v_lshl_add_u64 v[4:5], v[2:3], 1, s[18:19]
	global_load_lds_dwordx4 v[4:5], off
	s_add_i32 m0, s6, 0x1c000
	v_lshl_add_u64 v[4:5], v[48:49], 0, s[24:25]
	global_load_lds_dwordx4 v[4:5], off
	s_add_i32 m0, s6, 0x1e000
	v_lshl_add_u64 v[4:5], v[50:51], 0, s[24:25]
	global_load_lds_dwordx4 v[4:5], off
	s_add_i32 m0, s6, 0x20000
	v_lshl_add_u64 v[4:5], v[52:53], 0, s[24:25]
	global_load_lds_dwordx4 v[4:5], off
	v_mov_b32_e32 v2, v3
	v_mov_b32_e32 v4, v3
	v_mov_b32_e32 v5, v3
	v_mov_b64_e32 v[28:29], v[4:5]
	v_mov_b64_e32 v[24:25], v[4:5]
	v_mov_b64_e32 v[20:21], v[4:5]
	v_mov_b64_e32 v[16:17], v[4:5]
	v_mov_b64_e32 v[12:13], v[4:5]
	v_mov_b64_e32 v[8:9], v[4:5]
	v_mov_b64_e32 v[32:33], v[4:5]
	v_mov_b64_e32 v[36:37], v[4:5]
	v_mov_b64_e32 v[26:27], v[2:3]
	v_mov_b64_e32 v[22:23], v[2:3]
	v_mov_b64_e32 v[18:19], v[2:3]
	v_mov_b64_e32 v[14:15], v[2:3]
	v_mov_b64_e32 v[10:11], v[2:3]
	v_mov_b64_e32 v[6:7], v[2:3]
	v_mov_b64_e32 v[30:31], v[2:3]
	v_mov_b64_e32 v[34:35], v[2:3]
	s_and_saveexec_b64 s[6:7], s[4:5]
	s_cbranch_execz .LBB0_1527
	s_setprio 3
	ds_read_b128 v[4:7], v83 offset:32768
	ds_read_b128 v[8:11], v83 offset:34816
	ds_read_b128 v[12:15], v82
	ds_read_b128 v[16:19], v82 offset:2048
	ds_read_b128 v[28:31], v82 offset:4096
	ds_read_b128 v[32:35], v82 offset:6144
	ds_read_b128 v[102:105], v85 offset:32768
	s_waitcnt lgkmcnt(0)
	v_mfma_f32_16x16x32_bf16 v[20:23], v[4:7], v[12:15], 0
	v_mfma_f32_16x16x32_bf16 v[12:15], v[8:11], v[12:15], 0
	v_mfma_f32_16x16x32_bf16 v[24:27], v[4:7], v[16:19], 0
	v_mfma_f32_16x16x32_bf16 v[16:19], v[8:11], v[16:19], 0
	v_mfma_f32_16x16x32_bf16 v[98:101], v[8:11], v[28:31], 0
	v_mfma_f32_16x16x32_bf16 v[106:109], v[8:11], v[32:35], 0
	ds_read_b128 v[110:113], v85 offset:34816
	ds_read_b128 v[8:11], v84
	ds_read_b128 v[114:117], v84 offset:2048
	v_mfma_f32_16x16x32_bf16 v[94:97], v[4:7], v[28:31], 0
	v_mfma_f32_16x16x32_bf16 v[4:7], v[4:7], v[32:35], 0
	s_waitcnt lgkmcnt(0)
	v_mfma_f32_16x16x32_bf16 v[34:37], v[102:105], v[8:11], v[20:23]
	v_mfma_f32_16x16x32_bf16 v[30:33], v[110:113], v[8:11], v[12:15]
	v_mfma_f32_16x16x32_bf16 v[26:29], v[102:105], v[114:117], v[24:27]
	v_mfma_f32_16x16x32_bf16 v[22:25], v[110:113], v[114:117], v[16:19]
	ds_read_b128 v[8:11], v84 offset:4096
	ds_read_b128 v[114:117], v84 offset:6144
	s_waitcnt lgkmcnt(0)
	v_mfma_f32_16x16x32_bf16 v[18:21], v[102:105], v[8:11], v[94:97]
	v_mfma_f32_16x16x32_bf16 v[14:17], v[110:113], v[8:11], v[98:101]
	v_mfma_f32_16x16x32_bf16 v[10:13], v[102:105], v[114:117], v[4:7]
	v_mfma_f32_16x16x32_bf16 v[6:9], v[110:113], v[114:117], v[106:109]
